# final out-projection epilogue: the second half-tile's residual loads issued at the epilogue start instead of behind the first half's 16 stores
# speedup vs baseline: 1.0010x; 1.0008x over previous
; #define LAS __attribute__((address_space(3)))
; __global__ void __launch_bounds__(NTHR, 2) hybrid_fwd(Args a) {
;     ...
;     const int tid = threadIdx.x, lane = tid & 63, wave = __builtin_amdgcn_readfirstlane(tid >> 6);
;     const int G = gridDim.x, bx = blockIdx.x;
;     const int vcu = (G % 8 == 0) ? (bx % 8) * (G / 8) + bx / 8 : bx;
;     const int gw = vcu * NWAVES + wave, NGW = G * NWAVES;
;     unsigned char* ws = a.ws;
;     float* MOD = (float*)(ws + WS_MOD); float* SWp = (float*)(ws + WS_SW); float* SSQ = (float*)(ws + WS_SSQ);
;     bf16_t* WAB = (bf16_t*)(ws + WS_WAB); bf16_t* WOAB = (bf16_t*)(ws + WS_WOAB); bf16_t* WC = (bf16_t*)(ws + WS_WC); bf16_t* WOC = (bf16_t*)(ws + WS_WOC);
;     bf16_t* H0 = (bf16_t*)(ws + WS_H0); bf16_t* Y = (bf16_t*)(ws + WS_Y);
;     bf16_t* Ub = (bf16_t*)(ws + WS_U); bf16_t* Gb = (bf16_t*)(ws + WS_G); bf16_t* UZb = (bf16_t*)(ws + WS_UZ); bf16_t* Vb = (bf16_t*)(ws + WS_V);
;     bf16_t* X1 = (bf16_t*)(ws + WS_X1); bf16_t* H1 = (bf16_t*)(ws + WS_H1);
;     bf16_t* Qb = (bf16_t*)(ws + WS_Q); bf16_t* Kb = (bf16_t*)(ws + WS_K); bf16_t* Zb = (bf16_t*)(ws + WS_Z); bf16_t* VTb = (bf16_t*)(ws + WS_VT); bf16_t* OZb = (bf16_t*)(ws + WS_OZ);
;     const int lo = a.ph_lo, hi = a.ph_hi;
;     ...
;     volatile LAS unsigned* bst = (volatile LAS unsigned*)(lds + LDS_BYTES - 64);
;     if (tid < 4) bst[tid] = 0u;
;     __syncthreads();
;     XcdBarrier xbar; xbar.bar = (unsigned*)(ws + WS_CTL); xbar.x = 0; xbar.st = bst;
;     if (hi - lo > 1) xbar = xcd_barrier_post((unsigned*)(ws + WS_CTL), bst);
_Z10hybrid_fwd4Args:
	s_load_dwordx2 s[54:55], s[0:1], 0x88
	s_load_dword s3, s[0:1], 0x90
	s_add_u32 s4, s0, 0x90
	s_addc_u32 s5, s1, 0
	v_readfirstlane_b32 s8, v0
	v_writelane_b32 v255, s4, 0
	s_mov_b32 s78, s2
	s_mov_b32 s84, s2
	v_writelane_b32 v255, s5, 1
	s_waitcnt lgkmcnt(0)
	s_and_b32 s4, s3, 7
	s_cmp_lg_u32 s4, 0
	s_cbranch_scc0 .LBB0_31
	s_load_dwordx2 s[52:53], s[0:1], 0x80
	v_cmp_gt_u32_e32 vcc, 4, v0
	s_and_saveexec_b64 s[4:5], vcc

; __device__ __forceinline__ void xcd_barrier_arrive(const XcdBarrier& b) {
;     asm volatile("s_waitcnt vmcnt(0)" ::: "memory");
;     __syncthreads();
;     if (threadIdx.x == 0) {
;         unsigned* bar = b.bar;
;         __builtin_amdgcn_s_waitcnt(0);
;         unsigned nloc = b.st[0], nx = b.st[1];
;         if (nloc == 0u) { xcd_barrier_complete(bar, b.x, nloc, nx); b.st[0] = nloc; b.st[1] = nx; }
.LBB0_19:
	s_or_b64 exec, exec, s[18:19]
	s_cmp_gt_i32 s55, 1
	s_cselect_b64 s[0:1], -1, 0
	s_and_b64 vcc, exec, s[0:1]
	s_cbranch_vccz .LBB0_46
	s_waitcnt vmcnt(0)
	v_cmp_eq_u32_e32 vcc, 0, v0
	s_barrier
	s_and_saveexec_b64 s[4:5], vcc
	s_cbranch_execz .LBB0_45
	s_add_i32 s6, 0, 0x23fc0
	v_mov_b32_e32 v1, s6
	s_waitcnt vmcnt(0) expcnt(0) lgkmcnt(0)
	ds_read_b32 v2, v1
	s_add_i32 s6, 0, 0x23fc4
	v_mov_b32_e32 v1, s6
	ds_read_b32 v1, v1
	s_waitcnt lgkmcnt(1)
	v_cmp_ne_u32_e32 vcc, 0, v2
	s_cbranch_vccnz .LBB0_37
	v_readlane_b32 s6, v255, 0
	v_readlane_b32 s7, v255, 1
	s_load_dwordx2 s[10:11], s[6:7], 0x4
	s_add_u32 s6, s52, 0x1000
	s_addc_u32 s7, s53, 0
	s_add_u32 s8, s52, 0x1100
	s_addc_u32 s9, s53, 0
	s_waitcnt lgkmcnt(0)
	s_mul_i32 s24, s10, s3
	s_add_u32 s10, s52, 0x1200
	s_mul_i32 s24, s24, s11
	s_addc_u32 s11, s53, 0
	s_add_u32 s12, s52, 0x1300
	s_addc_u32 s13, s53, 0
	s_mov_b32 s25, 1
	v_mov_b32_e32 v17, 0
	s_branch .LBB0_24

; __device__ __forceinline__ void xcd_barrier(const XcdBarrier& b) {
;     asm volatile("s_waitcnt vmcnt(0)" ::: "memory");
;     __syncthreads();
;     if (threadIdx.x == 0) {
;         unsigned* bar = b.bar;
;         __builtin_amdgcn_s_waitcnt(0);
;         unsigned nloc = b.st[0], nx = b.st[1];
;         if (nloc == 0u) { xcd_barrier_complete(bar, b.x, nloc, nx); b.st[0] = nloc; b.st[1] = nx; }
.LBB0_128:
	s_cmp_gt_i32 s55, 2
	s_cselect_b64 s[10:11], -1, 0
	s_and_b64 s[0:1], s[0:1], s[10:11]
	s_andn2_b64 vcc, exec, s[0:1]
	s_cbranch_vccnz .LBB0_178
	s_waitcnt vmcnt(0)
	v_cmp_eq_u32_e32 vcc, 0, v0
	s_waitcnt lgkmcnt(0)
	s_barrier
	s_and_saveexec_b64 s[0:1], vcc
	s_cbranch_execz .LBB0_177
	s_add_i32 s6, 0, 0x23fc0
	v_mov_b32_e32 v1, s6
	s_waitcnt vmcnt(0) expcnt(0) lgkmcnt(0)
	ds_read_b32 v3, v1
	s_add_i32 s6, 0, 0x23fc4
	v_mov_b32_e32 v1, s6
	ds_read_b32 v1, v1
	s_waitcnt lgkmcnt(1)
	v_cmp_ne_u32_e32 vcc, 0, v3
	s_cbranch_vccnz .LBB0_145
	v_readlane_b32 s6, v255, 0
	v_readlane_b32 s7, v255, 1
	s_load_dwordx2 s[14:15], s[6:7], 0x4
	s_add_u32 s6, s52, 0x1000
	s_addc_u32 s7, s53, 0
	s_add_u32 s12, s52, 0x1100
	s_addc_u32 s13, s53, 0
	s_waitcnt lgkmcnt(0)
	s_mul_i32 s35, s14, s3
	s_add_u32 s14, s52, 0x1200
	s_mul_i32 s35, s35, s15
	s_addc_u32 s15, s53, 0
	s_add_u32 s18, s52, 0x1300
	s_addc_u32 s19, s53, 0
	s_mov_b32 s36, 1
	v_mov_b32_e32 v17, 0
	s_branch .LBB0_133

; __device__ __forceinline__ void xcd_barrier(const XcdBarrier& b) {
;     asm volatile("s_waitcnt vmcnt(0)" ::: "memory");
;     __syncthreads();
;     if (threadIdx.x == 0) {
;         unsigned* bar = b.bar;
;         __builtin_amdgcn_s_waitcnt(0);
;         unsigned nloc = b.st[0], nx = b.st[1];
;         if (nloc == 0u) { xcd_barrier_complete(bar, b.x, nloc, nx); b.st[0] = nloc; b.st[1] = nx; }
.LBB0_217:
	s_cmp_gt_i32 s55, 3
	s_cselect_b64 s[0:1], -1, 0
	s_and_b64 s[10:11], s[10:11], s[0:1]
	s_andn2_b64 vcc, exec, s[10:11]
	s_cbranch_vccnz .LBB0_267
	s_waitcnt vmcnt(0)
	v_cmp_eq_u32_e32 vcc, 0, v0
	s_waitcnt vmcnt(0) lgkmcnt(0)
	s_barrier
	s_and_saveexec_b64 s[10:11], vcc
	s_cbranch_execz .LBB0_266
	s_add_i32 s12, 0, 0x23fc0
	v_mov_b32_e32 v1, s12
	s_waitcnt vmcnt(0) expcnt(0) lgkmcnt(0)
	ds_read_b32 v3, v1
	s_add_i32 s12, 0, 0x23fc4
	v_mov_b32_e32 v1, s12
	ds_read_b32 v1, v1
	s_waitcnt lgkmcnt(1)
	v_cmp_ne_u32_e32 vcc, 0, v3
	s_cbranch_vccnz .LBB0_234
	v_readlane_b32 s12, v255, 0
	v_readlane_b32 s13, v255, 1
	s_load_dwordx2 s[18:19], s[12:13], 0x4
	s_add_u32 s12, s52, 0x1000
	s_addc_u32 s13, s53, 0
	s_add_u32 s14, s52, 0x1100
	s_addc_u32 s15, s53, 0
	s_waitcnt lgkmcnt(0)
	s_mul_i32 s35, s18, s3
	s_add_u32 s18, s52, 0x1200
	s_mul_i32 s35, s35, s19
	s_addc_u32 s19, s53, 0
	s_add_u32 s22, s52, 0x1300
	s_addc_u32 s23, s53, 0
	s_mov_b32 s40, 1
	v_mov_b32_e32 v17, 0
	s_branch .LBB0_222

; __device__ __forceinline__ void xcd_barrier(const XcdBarrier& b) {
;     asm volatile("s_waitcnt vmcnt(0)" ::: "memory");
;     __syncthreads();
;     if (threadIdx.x == 0) {
;         unsigned* bar = b.bar;
;         __builtin_amdgcn_s_waitcnt(0);
;         unsigned nloc = b.st[0], nx = b.st[1];
;         if (nloc == 0u) { xcd_barrier_complete(bar, b.x, nloc, nx); b.st[0] = nloc; b.st[1] = nx; }
.LBB0_292:
	s_cmp_gt_i32 s55, 4
	s_cselect_b64 s[0:1], -1, 0
	s_and_b64 s[10:11], s[10:11], s[0:1]
	s_andn2_b64 vcc, exec, s[10:11]
	s_cbranch_vccnz .LBB0_342
	s_waitcnt vmcnt(0)
	v_cmp_eq_u32_e32 vcc, 0, v0
	s_waitcnt vmcnt(0) lgkmcnt(0)
	s_barrier
	s_and_saveexec_b64 s[10:11], vcc
	s_cbranch_execz .LBB0_341
	s_add_i32 s12, 0, 0x23fc0
	v_mov_b32_e32 v1, s12
	s_waitcnt vmcnt(0) expcnt(0) lgkmcnt(0)
	ds_read_b32 v3, v1
	s_add_i32 s12, 0, 0x23fc4
	v_mov_b32_e32 v1, s12
	ds_read_b32 v1, v1
	s_waitcnt lgkmcnt(1)
	v_cmp_ne_u32_e32 vcc, 0, v3
	s_cbranch_vccnz .LBB0_309
	v_readlane_b32 s12, v255, 0
	v_readlane_b32 s13, v255, 1
	s_load_dwordx2 s[18:19], s[12:13], 0x4
	s_add_u32 s12, s52, 0x1000
	s_addc_u32 s13, s53, 0
	s_add_u32 s14, s52, 0x1100
	s_addc_u32 s15, s53, 0
	s_waitcnt lgkmcnt(0)
	s_mul_i32 s30, s18, s3
	s_add_u32 s18, s52, 0x1200
	s_mul_i32 s30, s30, s19
	s_addc_u32 s19, s53, 0
	s_add_u32 s22, s52, 0x1300
	s_addc_u32 s23, s53, 0
	s_mov_b32 s31, 1
	v_mov_b32_e32 v17, 0
	s_branch .LBB0_297

; __device__ __forceinline__ void xcd_barrier(const XcdBarrier& b) {
;     asm volatile("s_waitcnt vmcnt(0)" ::: "memory");
;     __syncthreads();
;     if (threadIdx.x == 0) {
;         unsigned* bar = b.bar;
;         __builtin_amdgcn_s_waitcnt(0);
;         unsigned nloc = b.st[0], nx = b.st[1];
;         if (nloc == 0u) { xcd_barrier_complete(bar, b.x, nloc, nx); b.st[0] = nloc; b.st[1] = nx; }
.LBB0_385:
	s_cmp_gt_i32 s55, 6
	s_cselect_b64 s[0:1], -1, 0
	s_and_b64 s[8:9], s[12:13], s[0:1]
	s_andn2_b64 vcc, exec, s[8:9]
	s_cbranch_vccnz .LBB0_435
	s_waitcnt vmcnt(0)
	v_cmp_eq_u32_e32 vcc, 0, v0
	s_waitcnt vmcnt(0) lgkmcnt(0)
	s_barrier
	s_and_saveexec_b64 s[8:9], vcc
	s_cbranch_execz .LBB0_434
	s_add_i32 s12, 0, 0x23fc0
	v_mov_b32_e32 v1, s12
	s_waitcnt vmcnt(0) expcnt(0) lgkmcnt(0)
	ds_read_b32 v3, v1
	s_add_i32 s12, 0, 0x23fc4
	v_mov_b32_e32 v1, s12
	ds_read_b32 v1, v1
	s_waitcnt lgkmcnt(1)
	v_cmp_ne_u32_e32 vcc, 0, v3
	s_cbranch_vccnz .LBB0_402
	v_readlane_b32 s12, v255, 0
	v_readlane_b32 s13, v255, 1
	s_load_dwordx2 s[16:17], s[12:13], 0x4
	s_add_u32 s12, s52, 0x1000
	s_addc_u32 s13, s53, 0
	s_add_u32 s14, s52, 0x1100
	s_addc_u32 s15, s53, 0
	s_waitcnt lgkmcnt(0)
	s_mul_i32 s26, s16, s3
	s_add_u32 s16, s52, 0x1200
	s_mul_i32 s26, s26, s17
	s_addc_u32 s17, s53, 0
	s_add_u32 s18, s52, 0x1300
	s_addc_u32 s19, s53, 0
	s_mov_b32 s27, 1
	v_mov_b32_e32 v17, 0
	s_branch .LBB0_390

; __device__ __forceinline__ void xcd_barrier(const XcdBarrier& b) {
;     asm volatile("s_waitcnt vmcnt(0)" ::: "memory");
;     __syncthreads();
;     if (threadIdx.x == 0) {
;         unsigned* bar = b.bar;
;         __builtin_amdgcn_s_waitcnt(0);
;         unsigned nloc = b.st[0], nx = b.st[1];
;         if (nloc == 0u) { xcd_barrier_complete(bar, b.x, nloc, nx); b.st[0] = nloc; b.st[1] = nx; }
.LBB0_486:
	s_cmp_gt_i32 s55, 7
	s_cselect_b64 s[0:1], -1, 0
	s_and_b64 s[4:5], s[8:9], s[0:1]
	s_andn2_b64 vcc, exec, s[4:5]
	s_cbranch_vccnz .LBB0_536
	s_waitcnt vmcnt(0)
	v_cmp_eq_u32_e32 vcc, 0, v0
	s_waitcnt vmcnt(0) lgkmcnt(0)
	s_barrier
	s_and_saveexec_b64 s[4:5], vcc
	s_cbranch_execz .LBB0_535
	s_add_i32 s8, 0, 0x23fc0
	v_mov_b32_e32 v1, s8
	s_waitcnt vmcnt(0) expcnt(0) lgkmcnt(0)
	ds_read_b32 v3, v1
	s_add_i32 s8, 0, 0x23fc4
	v_mov_b32_e32 v1, s8
	ds_read_b32 v1, v1
	s_waitcnt lgkmcnt(1)
	v_cmp_ne_u32_e32 vcc, 0, v3
	s_cbranch_vccnz .LBB0_503
	v_readlane_b32 s8, v255, 0
	v_readlane_b32 s9, v255, 1
	s_load_dwordx2 s[12:13], s[8:9], 0x4
	s_add_u32 s8, s52, 0x1000
	s_addc_u32 s9, s53, 0
	s_add_u32 s10, s52, 0x1100
	s_addc_u32 s11, s53, 0
	s_waitcnt lgkmcnt(0)
	s_mul_i32 s22, s12, s3
	s_add_u32 s12, s52, 0x1200
	s_mul_i32 s22, s22, s13
	s_addc_u32 s13, s53, 0
	s_add_u32 s14, s52, 0x1300
	s_addc_u32 s15, s53, 0
	s_mov_b32 s23, 1
	v_mov_b32_e32 v17, 0
	s_branch .LBB0_491

; __device__ __forceinline__ void xcd_barrier(const XcdBarrier& b) {
;     asm volatile("s_waitcnt vmcnt(0)" ::: "memory");
;     __syncthreads();
;     if (threadIdx.x == 0) {
;         unsigned* bar = b.bar;
;         __builtin_amdgcn_s_waitcnt(0);
;         unsigned nloc = b.st[0], nx = b.st[1];
;         if (nloc == 0u) { xcd_barrier_complete(bar, b.x, nloc, nx); b.st[0] = nloc; b.st[1] = nx; }
.LBB0_557:
	s_cmp_gt_i32 s55, 8
	s_cselect_b64 s[0:1], -1, 0
	s_and_b64 s[4:5], s[70:71], s[0:1]
	s_andn2_b64 vcc, exec, s[4:5]
	s_cbranch_vccnz .LBB0_607
	s_waitcnt vmcnt(0)
	v_cmp_eq_u32_e32 vcc, 0, v0
	s_waitcnt vmcnt(0) lgkmcnt(0)
	s_barrier
	s_and_saveexec_b64 s[4:5], vcc
	s_cbranch_execz .LBB0_606
	s_add_i32 s6, 0, 0x23fc0
	v_mov_b32_e32 v1, s6
	s_waitcnt vmcnt(0) expcnt(0) lgkmcnt(0)
	ds_read_b32 v3, v1
	s_add_i32 s6, 0, 0x23fc4
	v_mov_b32_e32 v1, s6
	ds_read_b32 v1, v1
	s_waitcnt lgkmcnt(1)
	v_cmp_ne_u32_e32 vcc, 0, v3
	s_cbranch_vccnz .LBB0_574
	v_readlane_b32 s6, v255, 0
	v_readlane_b32 s7, v255, 1
	s_load_dwordx2 s[10:11], s[6:7], 0x4
	s_add_u32 s6, s52, 0x1000
	s_addc_u32 s7, s53, 0
	s_add_u32 s8, s52, 0x1100
	s_addc_u32 s9, s53, 0
	s_waitcnt lgkmcnt(0)
	s_mul_i32 s20, s10, s3
	s_add_u32 s10, s52, 0x1200
	s_mul_i32 s20, s20, s11
	s_addc_u32 s11, s53, 0
	s_add_u32 s12, s52, 0x1300
	s_addc_u32 s13, s53, 0
	s_mov_b32 s21, 1
	v_mov_b32_e32 v17, 0
	s_branch .LBB0_562

;     __device__ bool next(int i, Unit& u) const {
;         const int L = i * G + c;
; __global__ void __launch_bounds__(NTHR, 2) hybrid_fwd(Args a) {
;     ...
;     if (IN(8)) { pg8::Sched2 S; S.init(OZb, WOC, M, D, nullptr, nullptr, 0, 0, D, G, bx);
;         pg8::EpiRes<false> E{X1, a.out, MOD + 2 * 3072 + 2048, nullptr, nullptr, nullptr, nullptr}; pg8::gemm_phase<pg8::EpiRes<false>, true, true>(lds, S, E); }
.LBB0_607:
	s_cmp_lt_i32 s54, 9
	s_cselect_b64 s[4:5], -1, 0
	s_and_b64 s[0:1], s[4:5], s[0:1]
	s_andn2_b64 vcc, exec, s[0:1]
	s_cbranch_vccnz .LBB0_632
	s_mov_b64 s[100:101], 0x40000
	s_cmpk_gt_i32 s2, 0xff
	v_readfirstlane_b32 s7, v0
	s_cbranch_scc1 .LBB0_632
	s_ashr_i32 s0, s2, 31
	s_lshr_b32 s0, s0, 29
	s_add_i32 s6, s2, s0
	s_and_b32 s0, s6, -8
	s_sub_i32 s4, s2, s0
	s_cmp_gt_i32 s4, -1
	s_cbranch_scc0 .LBB0_611
	s_lshl_b32 s5, s4, 5
	s_ashr_i32 s0, s6, 3
	s_cbranch_execz .LBB0_612
	s_branch .LBB0_613

; __device__ __forceinline__ float bf_lo(unsigned u) { return __uint_as_float(u << 16); }
;     __device__ __forceinline__ void operator()(const f32x4 (&acc)[2][2][4][2], const Unit& u, int wr, int wc, int fr, int fq) const {
;         const int row0 = u.pm * BM + wr * 64 + fr, col0 = u.pn * BM + wc * 32 + 8 * fq, bt = (u.pm * BM) / SEQ;
;         f32x4 gv[2][2], mv[2][2];
; #pragma unroll
;         for (int bj = 0; bj < 2; ++bj)
; #pragma unroll
;             for (int n = 0; n < 2; ++n) { gv[bj][n] = *(const f32x4*)(gate + bt * 3072 + col0 + bj * HALF + 4 * n);
;                 if (STATS) mv[bj][n] = *(const f32x4*)(lng + col0 + bj * HALF + 4 * n) * (*(const f32x4*)(scale + bt * 3072 + col0 + bj * HALF + 4 * n) + 1.0f); }
;         constexpr int MB = STATS ? 2 : 4;
; #pragma unroll
;         for (int ai = 0; ai < 2; ++ai)
; #pragma unroll
;         for (int mb = 0; mb < 4; mb += MB) {
;             f32x4 bf[MB][2][2]; u32x4 bh[MB][2];
; #pragma unroll
;             for (int mm = 0; mm < MB; ++mm) { const size_t off = (size_t)(row0 + ai * HALF + (mb + mm) * 16) * D + col0;
; #pragma unroll
;                 for (int bj = 0; bj < 2; ++bj) {
;                     if (STATS) { bf[mm][bj][0] = *(const f32x4*)((const float*)base + off + bj * HALF); bf[mm][bj][1] = *(const f32x4*)((const float*)base + off + bj * HALF + 4); }
;                     else bh[mm][bj] = *(const u32x4*)((const bf16_t*)base + off + bj * HALF); } }
; #pragma unroll
;             for (int mm = 0; mm < MB; ++mm) { const int m = mb + mm; const int row = row0 + ai * HALF + m * 16; const size_t off = (size_t)row * D + col0; float ss = 0.f;
; #pragma unroll
;                 for (int bj = 0; bj < 2; ++bj) { f32x4 b0, b1;
;                     if (STATS) { b0 = bf[mm][bj][0]; b1 = bf[mm][bj][1]; }
;                     else { const u32x4 t = bh[mm][bj]; b0 = (f32x4){bf_lo(t.x), bf_hi(t.x), bf_lo(t.y), bf_hi(t.y)}; b1 = (f32x4){bf_lo(t.z), bf_hi(t.z), bf_lo(t.w), bf_hi(t.w)}; }
;                     const f32x4 o0 = b0 + gv[bj][0] * acc[ai][bj][m][0], o1 = b1 + gv[bj][1] * acc[ai][bj][m][1];
;                     if (STATS) { u32x4 w; w.x = cvt_pk_bf16(o0[0], o0[1]); w.y = cvt_pk_bf16(o0[2], o0[3]); w.z = cvt_pk_bf16(o1[0], o1[1]); w.w = cvt_pk_bf16(o1[2], o1[3]);
;                         *(u32x4*)((bf16_t*)out + off + bj * HALF) = w;
.LBB0_628:
	s_ashr_i32 s11, s18, 31
	s_lshr_b32 s11, s11, 27
	s_add_i32 s11, s18, s11
	s_lshr_b32 s11, s11, 5
	v_lshl_or_b32 v128, s38, 8, v166
	v_lshl_add_u32 v160, s18, 8, v164
	s_mul_i32 s20, s11, 0xc00
	v_ashrrev_i32_e32 v129, 31, v128
	v_ashrrev_i32_e32 v161, 31, v160
	s_ashr_i32 s21, s20, 31
	v_lshl_add_u64 v[158:159], v[128:129], 1, s[60:61]
	v_lshlrev_b64 v[130:131], 11, v[160:161]
	v_or_b32_e32 v190, 16, v160
	s_lshl_b64 s[20:21], s[20:21], 2
	v_lshl_add_u64 v[130:131], v[158:159], 0, v[130:131]
	v_ashrrev_i32_e32 v191, 31, v190
	s_add_u32 s20, s31, s20
	global_load_dwordx4 v[170:173], v[130:131], off
	global_load_dwordx4 v[174:177], v[130:131], off offset:256
	v_lshl_add_u64 v[222:223], v[130:131], 0, s[100:101]
	global_load_dwordx4 v[226:229], v[222:223], off offset:256
	global_load_dwordx4 v[222:225], v[222:223], off
	v_lshlrev_b64 v[130:131], 11, v[190:191]
	v_lshlrev_b64 v[156:157], 2, v[128:129]
	s_addc_u32 s21, s33, s21
	v_lshl_add_u64 v[130:131], v[158:159], 0, v[130:131]
	v_lshl_add_u64 v[128:129], s[20:21], 0, v[156:157]
	v_or_b32_e32 v202, 32, v160
	global_load_dwordx4 v[178:181], v[130:131], off
	global_load_dwordx4 v[182:185], v[130:131], off offset:256
	v_lshl_add_u64 v[230:231], v[130:131], 0, s[100:101]
	global_load_dwordx4 v[234:237], v[230:231], off offset:256
	global_load_dwordx4 v[230:233], v[230:231], off
	global_load_dwordx4 v[140:143], v[128:129], off
	global_load_dwordx4 v[136:139], v[128:129], off offset:16
	global_load_dwordx4 v[132:135], v[128:129], off offset:512
	s_nop 0
	global_load_dwordx4 v[128:131], v[128:129], off offset:528
	v_ashrrev_i32_e32 v203, 31, v202
	v_lshlrev_b64 v[162:163], 11, v[202:203]
	v_lshl_add_u64 v[192:193], v[158:159], 0, v[162:163]
	global_load_dwordx4 v[186:189], v[192:193], off
	v_lshl_add_u64 v[238:239], v[192:193], 0, s[100:101]
	global_load_dwordx4 v[242:245], v[238:239], off offset:256
	global_load_dwordx4 v[238:241], v[238:239], off
	v_or_b32_e32 v162, 48, v160
	v_ashrrev_i32_e32 v163, 31, v162
	v_lshlrev_b64 v[198:199], 12, v[190:191]
	global_load_dwordx4 v[190:193], v[192:193], off offset:256
	v_lshlrev_b64 v[194:195], 12, v[160:161]
	v_lshlrev_b64 v[196:197], 11, v[162:163]
	v_lshl_add_u64 v[194:195], s[50:51], 0, v[194:195]
	v_lshl_add_u64 v[200:201], v[158:159], 0, v[196:197]
	v_lshl_add_u64 v[204:205], v[194:195], 0, v[156:157]
	v_lshl_add_u64 v[206:207], s[50:51], 0, v[198:199]
	global_load_dwordx4 v[194:197], v[200:201], off
	v_lshl_add_u64 v[246:247], v[200:201], 0, s[100:101]
	global_load_dwordx4 v[250:253], v[246:247], off offset:256
	global_load_dwordx4 v[246:249], v[246:247], off
	s_nop 0
	global_load_dwordx4 v[198:201], v[200:201], off offset:256
	v_lshl_add_u64 v[206:207], v[206:207], 0, v[156:157]
	s_andn2_b64 vcc, exec, s[8:9]
	s_mov_b64 s[8:9], -1
	s_waitcnt vmcnt(0)
	v_lshlrev_b32_e32 v208, 16, v170
	v_and_b32_e32 v209, 0xffff0000, v170
	v_lshlrev_b32_e32 v170, 16, v171
	v_and_b32_e32 v171, 0xffff0000, v171
	v_lshlrev_b32_e32 v214, 16, v176
	v_and_b32_e32 v215, 0xffff0000, v176
	v_lshlrev_b32_e32 v176, 16, v177
	v_and_b32_e32 v177, 0xffff0000, v177
	v_lshlrev_b32_e32 v210, 16, v172
	v_and_b32_e32 v211, 0xffff0000, v172
	v_lshlrev_b32_e32 v172, 16, v173
	v_and_b32_e32 v173, 0xffff0000, v173
	v_lshlrev_b32_e32 v212, 16, v174
	v_and_b32_e32 v213, 0xffff0000, v174
	v_lshlrev_b32_e32 v174, 16, v175
	v_and_b32_e32 v175, 0xffff0000, v175
	v_lshlrev_b32_e32 v216, 16, v178
	v_and_b32_e32 v217, 0xffff0000, v178
	v_lshlrev_b32_e32 v178, 16, v179
	v_and_b32_e32 v179, 0xffff0000, v179
	v_lshlrev_b32_e32 v218, 16, v180
	v_and_b32_e32 v219, 0xffff0000, v180
	v_lshlrev_b32_e32 v180, 16, v181
	v_and_b32_e32 v181, 0xffff0000, v181
	v_pk_fma_f32 v[124:125], v[124:125], v[140:141], v[208:209]
	v_pk_fma_f32 v[126:127], v[126:127], v[142:143], v[170:171]
	v_pk_fma_f32 v[104:105], v[104:105], v[128:129], v[214:215]
	v_pk_fma_f32 v[106:107], v[106:107], v[130:131], v[176:177]
	v_lshlrev_b32_e32 v220, 16, v182
	v_and_b32_e32 v221, 0xffff0000, v182
	v_pk_fma_f32 v[120:121], v[120:121], v[136:137], v[210:211]
	v_pk_fma_f32 v[122:123], v[122:123], v[138:139], v[172:173]
	v_pk_fma_f32 v[108:109], v[108:109], v[132:133], v[212:213]
	v_pk_fma_f32 v[110:111], v[110:111], v[134:135], v[174:175]
	v_pk_fma_f32 v[116:117], v[116:117], v[140:141], v[216:217]
	v_pk_fma_f32 v[118:119], v[118:119], v[142:143], v[178:179]
	v_pk_fma_f32 v[112:113], v[112:113], v[136:137], v[218:219]
	v_pk_fma_f32 v[114:115], v[114:115], v[138:139], v[180:181]
	global_store_dwordx4 v[204:205], v[124:127], off
	global_store_dwordx4 v[204:205], v[120:123], off offset:16
	global_store_dwordx4 v[204:205], v[108:111], off offset:512
	global_store_dwordx4 v[204:205], v[104:107], off offset:528
	global_store_dwordx4 v[206:207], v[116:119], off
	global_store_dwordx4 v[206:207], v[112:115], off offset:16
	v_lshlrev_b32_e32 v104, 16, v183
	v_and_b32_e32 v105, 0xffff0000, v183
	v_lshlrev_b32_e32 v106, 16, v184
	v_and_b32_e32 v107, 0xffff0000, v184
	v_lshlrev_b32_e32 v108, 16, v185
	v_and_b32_e32 v109, 0xffff0000, v185
	v_pk_fma_f32 v[100:101], v[100:101], v[132:133], v[220:221]
	v_pk_fma_f32 v[102:103], v[102:103], v[134:135], v[104:105]
	v_pk_fma_f32 v[92:93], v[92:93], v[128:129], v[106:107]
	v_pk_fma_f32 v[94:95], v[94:95], v[130:131], v[108:109]
	global_store_dwordx4 v[206:207], v[100:103], off offset:512
	global_store_dwordx4 v[206:207], v[92:95], off offset:528
	s_nop 0
	v_lshlrev_b32_e32 v100, 16, v188
	v_lshlrev_b32_e32 v92, 16, v186
	v_and_b32_e32 v93, 0xffff0000, v186
	v_pk_fma_f32 v[92:93], v[96:97], v[140:141], v[92:93]
	v_lshlrev_b64 v[96:97], 12, v[202:203]
	v_lshlrev_b32_e32 v94, 16, v187
; __device__ __forceinline__ unsigned cvt_pk_bf16(float lo, float hi) { f32x2_t v = {lo, hi}; bf16x2_t b = __builtin_convertvector(v, bf16x2_t); return __builtin_bit_cast(unsigned, b); }
; __device__ __forceinline__ float bf_lo(unsigned u) { return __uint_as_float(u << 16); }
; __device__ __forceinline__ float bf_hi(unsigned u) { return __uint_as_float(u & 0xffff0000u); }
;     __device__ __forceinline__ void operator()(const f32x4 (&acc)[2][2][4][2], const Unit& u, int wr, int wc, int fr, int fq) const {
;     ...
;             for (int mm = 0; mm < MB; ++mm) { const int m = mb + mm; const int row = row0 + ai * HALF + m * 16; const size_t off = (size_t)row * D + col0; float ss = 0.f;
; #pragma unroll
;                 for (int bj = 0; bj < 2; ++bj) { f32x4 b0, b1;
;                     if (STATS) { b0 = bf[mm][bj][0]; b1 = bf[mm][bj][1]; }
;                     else { const u32x4 t = bh[mm][bj]; b0 = (f32x4){bf_lo(t.x), bf_hi(t.x), bf_lo(t.y), bf_hi(t.y)}; b1 = (f32x4){bf_lo(t.z), bf_hi(t.z), bf_lo(t.w), bf_hi(t.w)}; }
;                     const f32x4 o0 = b0 + gv[bj][0] * acc[ai][bj][m][0], o1 = b1 + gv[bj][1] * acc[ai][bj][m][1];
;                     if (STATS) { u32x4 w; w.x = cvt_pk_bf16(o0[0], o0[1]); w.y = cvt_pk_bf16(o0[2], o0[3]); w.z = cvt_pk_bf16(o1[0], o1[1]); w.w = cvt_pk_bf16(o1[2], o1[3]);
;                         *(u32x4*)((bf16_t*)out + off + bj * HALF) = w;
;                         ss += (o0[0] * o0[0] + o0[1] * o0[1]) + (o0[2] * o0[2] + o0[3] * o0[3]) + (o1[0] * o1[0] + o1[1] * o1[1]) + (o1[2] * o1[2] + o1[3] * o1[3]);
;                         const f32x4 x0 = o0 * mv[bj][0], x1 = o1 * mv[bj][1];
;                         u32x4 w2; w2.x = cvt_pk_bf16(x0[0], x0[1]); w2.y = cvt_pk_bf16(x0[2], x0[3]); w2.z = cvt_pk_bf16(x1[0], x1[1]); w2.w = cvt_pk_bf16(x1[2], x1[3]);
;                         *(u32x4*)(xm + off + bj * HALF) = w2; }
;                     else { *(f32x4*)((float*)out + off + bj * HALF) = o0; *(f32x4*)((float*)out + off + bj * HALF + 4) = o1; } }
	v_and_b32_e32 v95, 0xffff0000, v187
	v_and_b32_e32 v101, 0xffff0000, v188
	v_lshlrev_b32_e32 v102, 16, v189
	v_and_b32_e32 v103, 0xffff0000, v189
	v_lshl_add_u64 v[96:97], s[50:51], 0, v[96:97]
	v_pk_fma_f32 v[94:95], v[98:99], v[142:143], v[94:95]
	v_pk_fma_f32 v[88:89], v[88:89], v[136:137], v[100:101]
	v_pk_fma_f32 v[90:91], v[90:91], v[138:139], v[102:103]
	v_lshl_add_u64 v[96:97], v[96:97], 0, v[156:157]
	global_store_dwordx4 v[96:97], v[92:95], off
	global_store_dwordx4 v[96:97], v[88:91], off offset:16
	v_add_u32_e32 v98, 0x90, v160
	v_lshlrev_b32_e32 v92, 16, v192
	v_lshlrev_b32_e32 v88, 16, v190
	v_and_b32_e32 v89, 0xffff0000, v190
	v_lshlrev_b32_e32 v90, 16, v191
	v_and_b32_e32 v91, 0xffff0000, v191
	v_and_b32_e32 v93, 0xffff0000, v192
	v_lshlrev_b32_e32 v94, 16, v193
	v_and_b32_e32 v95, 0xffff0000, v193
	v_pk_fma_f32 v[84:85], v[84:85], v[132:133], v[88:89]
	v_pk_fma_f32 v[86:87], v[86:87], v[134:135], v[90:91]
	v_pk_fma_f32 v[76:77], v[76:77], v[128:129], v[92:93]
	v_pk_fma_f32 v[78:79], v[78:79], v[130:131], v[94:95]
	global_store_dwordx4 v[96:97], v[84:87], off offset:512
	global_store_dwordx4 v[96:97], v[76:79], off offset:528
	v_add_u32_e32 v96, 0x80, v160
	v_lshlrev_b32_e32 v84, 16, v196
	v_lshlrev_b32_e32 v76, 16, v194
	v_and_b32_e32 v77, 0xffff0000, v194
	v_pk_fma_f32 v[76:77], v[80:81], v[140:141], v[76:77]
	v_lshlrev_b64 v[80:81], 12, v[162:163]
	v_lshlrev_b32_e32 v78, 16, v195
	v_and_b32_e32 v79, 0xffff0000, v195
	v_and_b32_e32 v85, 0xffff0000, v196
	v_lshlrev_b32_e32 v86, 16, v197
	v_and_b32_e32 v87, 0xffff0000, v197
	v_lshl_add_u64 v[80:81], s[50:51], 0, v[80:81]
	v_pk_fma_f32 v[78:79], v[82:83], v[142:143], v[78:79]
	v_pk_fma_f32 v[72:73], v[72:73], v[136:137], v[84:85]
	v_pk_fma_f32 v[74:75], v[74:75], v[138:139], v[86:87]
	v_lshl_add_u64 v[80:81], v[80:81], 0, v[156:157]
	global_store_dwordx4 v[80:81], v[76:79], off
	global_store_dwordx4 v[80:81], v[72:75], off offset:16
	v_ashrrev_i32_e32 v97, 31, v96
	v_lshlrev_b32_e32 v76, 16, v200
	v_lshlrev_b32_e32 v72, 16, v198
	v_and_b32_e32 v73, 0xffff0000, v198
	v_lshlrev_b32_e32 v74, 16, v199
	v_and_b32_e32 v75, 0xffff0000, v199
	v_and_b32_e32 v77, 0xffff0000, v200
	v_lshlrev_b32_e32 v78, 16, v201
	v_and_b32_e32 v79, 0xffff0000, v201
	v_pk_fma_f32 v[68:69], v[68:69], v[132:133], v[72:73]
	v_pk_fma_f32 v[70:71], v[70:71], v[134:135], v[74:75]
	v_pk_fma_f32 v[64:65], v[64:65], v[128:129], v[76:77]
	v_pk_fma_f32 v[66:67], v[66:67], v[130:131], v[78:79]
	global_store_dwordx4 v[80:81], v[68:71], off offset:512
	global_store_dwordx4 v[80:81], v[64:67], off offset:528
	v_ashrrev_i32_e32 v99, 31, v98
	v_add_u32_e32 v100, 0xa0, v160
	v_lshlrev_b64 v[64:65], 11, v[96:97]
	v_lshl_add_u64 v[64:65], v[158:159], 0, v[64:65]
	v_lshlrev_b64 v[64:65], 11, v[98:99]
	v_lshl_add_u64 v[64:65], v[158:159], 0, v[64:65]
	v_ashrrev_i32_e32 v101, 31, v100
	v_lshlrev_b64 v[64:65], 11, v[100:101]
	v_lshl_add_u64 v[64:65], v[158:159], 0, v[64:65]
	v_add_u32_e32 v102, 0xb0, v160
	v_ashrrev_i32_e32 v103, 31, v102
	v_lshlrev_b64 v[64:65], 11, v[102:103]
	v_lshl_add_u64 v[64:65], v[158:159], 0, v[64:65]
	s_nop 0
	v_lshlrev_b32_e32 v104, 16, v222
	v_and_b32_e32 v105, 0xffff0000, v222
	v_lshlrev_b32_e32 v68, 16, v223
	v_and_b32_e32 v69, 0xffff0000, v223
	v_pk_fma_f32 v[62:63], v[62:63], v[142:143], v[68:69]
	v_lshlrev_b64 v[68:69], 12, v[96:97]
	v_lshlrev_b32_e32 v106, 16, v224
	v_and_b32_e32 v107, 0xffff0000, v224
	v_lshlrev_b32_e32 v70, 16, v225
	v_and_b32_e32 v71, 0xffff0000, v225
	v_lshl_add_u64 v[68:69], s[50:51], 0, v[68:69]
	v_pk_fma_f32 v[60:61], v[60:61], v[140:141], v[104:105]
	v_pk_fma_f32 v[58:59], v[58:59], v[138:139], v[70:71]
	v_pk_fma_f32 v[56:57], v[56:57], v[136:137], v[106:107]
	v_lshl_add_u64 v[68:69], v[68:69], 0, v[156:157]
	global_store_dwordx4 v[68:69], v[60:63], off
	global_store_dwordx4 v[68:69], v[56:59], off offset:16
	v_lshlrev_b32_e32 v60, 16, v228
	v_lshlrev_b32_e32 v56, 16, v226
	v_and_b32_e32 v57, 0xffff0000, v226
	v_lshlrev_b32_e32 v58, 16, v227
	v_and_b32_e32 v59, 0xffff0000, v227
	v_and_b32_e32 v61, 0xffff0000, v228
	v_lshlrev_b32_e32 v62, 16, v229
	v_and_b32_e32 v63, 0xffff0000, v229
	v_pk_fma_f32 v[54:55], v[54:55], v[134:135], v[58:59]
	v_pk_fma_f32 v[52:53], v[52:53], v[132:133], v[56:57]
	v_pk_fma_f32 v[44:45], v[44:45], v[128:129], v[60:61]
; __device__ __forceinline__ unsigned cvt_pk_bf16(float lo, float hi) { f32x2_t v = {lo, hi}; bf16x2_t b = __builtin_convertvector(v, bf16x2_t); return __builtin_bit_cast(unsigned, b); }
; template <class Epi, bool ALIGN_EPI, bool SP2>
; __device__ __forceinline__ void gemm_phase(LAS unsigned char* lds, const Sched2& S, const Epi& E) {
;     ...
;         if (!has_next) break;
; #pragma unroll
;         for (int a = 0; a < 2; ++a)
; #pragma unroll
;             for (int b = 0; b < 2; ++b)
; #pragma unroll
;                 for (int m = 0; m < 4; ++m)
; #pragma unroll
;                     for (int n = 0; n < 2; ++n) acc[a][b][m][n] = (f32x4){0.f, 0.f, 0.f, 0.f};
;         cur = nxt; cA = nA; cB = nB; ++ui;
;         if constexpr (ALIGN_EPI) { if (wr == 1) PG8_BAR; }
;     __device__ __forceinline__ void operator()(const f32x4 (&acc)[2][2][4][2], const Unit& u, int wr, int wc, int fr, int fq) const {
;     ...
;             for (int mm = 0; mm < MB; ++mm) { const int m = mb + mm; const int row = row0 + ai * HALF + m * 16; const size_t off = (size_t)row * D + col0; float ss = 0.f;
; #pragma unroll
;                 for (int bj = 0; bj < 2; ++bj) { f32x4 b0, b1;
;                     if (STATS) { b0 = bf[mm][bj][0]; b1 = bf[mm][bj][1]; }
;                     else { const u32x4 t = bh[mm][bj]; b0 = (f32x4){bf_lo(t.x), bf_hi(t.x), bf_lo(t.y), bf_hi(t.y)}; b1 = (f32x4){bf_lo(t.z), bf_hi(t.z), bf_lo(t.w), bf_hi(t.w)}; }
;                     const f32x4 o0 = b0 + gv[bj][0] * acc[ai][bj][m][0], o1 = b1 + gv[bj][1] * acc[ai][bj][m][1];
;                     if (STATS) { u32x4 w; w.x = cvt_pk_bf16(o0[0], o0[1]); w.y = cvt_pk_bf16(o0[2], o0[3]); w.z = cvt_pk_bf16(o1[0], o1[1]); w.w = cvt_pk_bf16(o1[2], o1[3]);
;                         *(u32x4*)((bf16_t*)out + off + bj * HALF) = w;
;                         ss += (o0[0] * o0[0] + o0[1] * o0[1]) + (o0[2] * o0[2] + o0[3] * o0[3]) + (o1[0] * o1[0] + o1[1] * o1[1]) + (o1[2] * o1[2] + o1[3] * o1[3]);
;                         const f32x4 x0 = o0 * mv[bj][0], x1 = o1 * mv[bj][1];
;                         u32x4 w2; w2.x = cvt_pk_bf16(x0[0], x0[1]); w2.y = cvt_pk_bf16(x0[2], x0[3]); w2.z = cvt_pk_bf16(x1[0], x1[1]); w2.w = cvt_pk_bf16(x1[2], x1[3]);
;                         *(u32x4*)(xm + off + bj * HALF) = w2; }
;                     else { *(f32x4*)((float*)out + off + bj * HALF) = o0; *(f32x4*)((float*)out + off + bj * HALF + 4) = o1; } }
	v_pk_fma_f32 v[46:47], v[46:47], v[130:131], v[62:63]
	global_store_dwordx4 v[68:69], v[52:55], off offset:512
	global_store_dwordx4 v[68:69], v[44:47], off offset:528
	v_lshlrev_b32_e32 v52, 16, v232
	v_lshlrev_b32_e32 v44, 16, v230
	v_and_b32_e32 v45, 0xffff0000, v230
	v_pk_fma_f32 v[44:45], v[48:49], v[140:141], v[44:45]
	v_lshlrev_b64 v[48:49], 12, v[98:99]
	v_lshlrev_b32_e32 v46, 16, v231
	v_and_b32_e32 v47, 0xffff0000, v231
	v_and_b32_e32 v53, 0xffff0000, v232
	v_lshlrev_b32_e32 v54, 16, v233
	v_and_b32_e32 v55, 0xffff0000, v233
	v_lshl_add_u64 v[48:49], s[50:51], 0, v[48:49]
	v_pk_fma_f32 v[46:47], v[50:51], v[142:143], v[46:47]
	v_pk_fma_f32 v[42:43], v[42:43], v[138:139], v[54:55]
	v_pk_fma_f32 v[40:41], v[40:41], v[136:137], v[52:53]
	v_lshl_add_u64 v[48:49], v[48:49], 0, v[156:157]
	global_store_dwordx4 v[48:49], v[44:47], off
	global_store_dwordx4 v[48:49], v[40:43], off offset:16
	v_lshlrev_b32_e32 v44, 16, v236
	v_lshlrev_b32_e32 v40, 16, v234
	v_and_b32_e32 v41, 0xffff0000, v234
	v_lshlrev_b32_e32 v42, 16, v235
	v_and_b32_e32 v43, 0xffff0000, v235
	v_and_b32_e32 v45, 0xffff0000, v236
	v_lshlrev_b32_e32 v46, 16, v237
	v_and_b32_e32 v47, 0xffff0000, v237
	v_pk_fma_f32 v[38:39], v[38:39], v[134:135], v[42:43]
	v_pk_fma_f32 v[36:37], v[36:37], v[132:133], v[40:41]
	v_pk_fma_f32 v[28:29], v[28:29], v[128:129], v[44:45]
	v_pk_fma_f32 v[30:31], v[30:31], v[130:131], v[46:47]
	global_store_dwordx4 v[48:49], v[36:39], off offset:512
	global_store_dwordx4 v[48:49], v[28:31], off offset:528
	v_lshlrev_b32_e32 v36, 16, v240
	v_lshlrev_b32_e32 v28, 16, v238
	v_and_b32_e32 v29, 0xffff0000, v238
	v_pk_fma_f32 v[28:29], v[32:33], v[140:141], v[28:29]
	v_lshlrev_b64 v[32:33], 12, v[100:101]
	v_lshlrev_b32_e32 v30, 16, v239
	v_and_b32_e32 v31, 0xffff0000, v239
	v_and_b32_e32 v37, 0xffff0000, v240
	v_lshlrev_b32_e32 v38, 16, v241
	v_and_b32_e32 v39, 0xffff0000, v241
	v_lshl_add_u64 v[32:33], s[50:51], 0, v[32:33]
	v_pk_fma_f32 v[30:31], v[34:35], v[142:143], v[30:31]
	v_pk_fma_f32 v[26:27], v[26:27], v[138:139], v[38:39]
	v_pk_fma_f32 v[24:25], v[24:25], v[136:137], v[36:37]
	v_lshl_add_u64 v[32:33], v[32:33], 0, v[156:157]
	global_store_dwordx4 v[32:33], v[28:31], off
	global_store_dwordx4 v[32:33], v[24:27], off offset:16
	v_lshlrev_b32_e32 v28, 16, v244
	v_lshlrev_b32_e32 v24, 16, v242
	v_and_b32_e32 v25, 0xffff0000, v242
	v_lshlrev_b32_e32 v26, 16, v243
	v_and_b32_e32 v27, 0xffff0000, v243
	v_and_b32_e32 v29, 0xffff0000, v244
	v_lshlrev_b32_e32 v30, 16, v245
	v_and_b32_e32 v31, 0xffff0000, v245
	v_pk_fma_f32 v[22:23], v[22:23], v[134:135], v[26:27]
	v_pk_fma_f32 v[20:21], v[20:21], v[132:133], v[24:25]
	v_pk_fma_f32 v[12:13], v[12:13], v[128:129], v[28:29]
	v_pk_fma_f32 v[14:15], v[14:15], v[130:131], v[30:31]
	global_store_dwordx4 v[32:33], v[20:23], off offset:512
	global_store_dwordx4 v[32:33], v[12:15], off offset:528
	v_lshlrev_b32_e32 v20, 16, v248
	v_lshlrev_b32_e32 v12, 16, v246
	v_and_b32_e32 v13, 0xffff0000, v246
	v_pk_fma_f32 v[12:13], v[16:17], v[140:141], v[12:13]
	v_lshlrev_b64 v[16:17], 12, v[102:103]
	v_lshlrev_b32_e32 v14, 16, v247
	v_and_b32_e32 v15, 0xffff0000, v247
	v_and_b32_e32 v21, 0xffff0000, v248
	v_lshlrev_b32_e32 v22, 16, v249
	v_and_b32_e32 v23, 0xffff0000, v249
	v_lshl_add_u64 v[16:17], s[50:51], 0, v[16:17]
	v_pk_fma_f32 v[14:15], v[18:19], v[142:143], v[14:15]
	v_pk_fma_f32 v[10:11], v[10:11], v[138:139], v[22:23]
	v_pk_fma_f32 v[8:9], v[8:9], v[136:137], v[20:21]
	v_lshl_add_u64 v[16:17], v[16:17], 0, v[156:157]
	global_store_dwordx4 v[16:17], v[12:15], off
	global_store_dwordx4 v[16:17], v[8:11], off offset:16
	v_lshlrev_b32_e32 v12, 16, v252
	v_lshlrev_b32_e32 v8, 16, v250
	v_and_b32_e32 v9, 0xffff0000, v250
	v_lshlrev_b32_e32 v10, 16, v251
	v_and_b32_e32 v11, 0xffff0000, v251
	v_and_b32_e32 v13, 0xffff0000, v252
	v_lshlrev_b32_e32 v14, 16, v253
	v_and_b32_e32 v15, 0xffff0000, v253
	v_pk_fma_f32 v[6:7], v[6:7], v[134:135], v[10:11]
	v_pk_fma_f32 v[4:5], v[4:5], v[132:133], v[8:9]
	v_pk_fma_f32 v[2:3], v[2:3], v[130:131], v[14:15]
	v_pk_fma_f32 v[0:1], v[0:1], v[128:129], v[12:13]
	global_store_dwordx4 v[16:17], v[4:7], off offset:512
	global_store_dwordx4 v[16:17], v[0:3], off offset:528
	s_cbranch_vccnz .LBB0_617
	s_andn2_b64 vcc, exec, s[0:1]
	s_cbranch_vccnz .LBB0_616
	s_barrier
	s_branch .LBB0_616

; __global__ void __launch_bounds__(NTHR, 2) hybrid_fwd(Args a) {
	.amdhsa_kernel _Z10hybrid_fwd4Args
		.amdhsa_group_segment_fixed_size 0
		.amdhsa_private_segment_fixed_size 0
		.amdhsa_kernarg_size 400
		.amdhsa_user_sgpr_count 2
		.amdhsa_user_sgpr_dispatch_ptr 0
		.amdhsa_user_sgpr_queue_ptr 0
		.amdhsa_user_sgpr_kernarg_segment_ptr 1
		.amdhsa_user_sgpr_dispatch_id 0
		.amdhsa_user_sgpr_kernarg_preload_length 0
		.amdhsa_user_sgpr_kernarg_preload_offset 0
		.amdhsa_user_sgpr_private_segment_size 0
		.amdhsa_uses_dynamic_stack 0
		.amdhsa_enable_private_segment 0
		.amdhsa_system_sgpr_workgroup_id_x 1
		.amdhsa_system_sgpr_workgroup_id_y 0
		.amdhsa_system_sgpr_workgroup_id_z 0
		.amdhsa_system_sgpr_workgroup_info 0
		.amdhsa_system_vgpr_workitem_id 0
		.amdhsa_next_free_vgpr 256
		.amdhsa_next_free_sgpr 102
		.amdhsa_accum_offset 256
		.amdhsa_reserve_vcc 1
		.amdhsa_float_round_mode_32 0
		.amdhsa_float_round_mode_16_64 0
		.amdhsa_float_denorm_mode_32 3
		.amdhsa_float_denorm_mode_16_64 3
		.amdhsa_dx10_clamp 1
		.amdhsa_ieee_mode 1
		.amdhsa_fp16_overflow 0
		.amdhsa_tg_split 0
		.amdhsa_exception_fp_ieee_invalid_op 0
		.amdhsa_exception_fp_denorm_src 0
		.amdhsa_exception_fp_ieee_div_zero 0
		.amdhsa_exception_fp_ieee_overflow 0
		.amdhsa_exception_fp_ieee_underflow 0
		.amdhsa_exception_fp_ieee_inexact 0
		.amdhsa_exception_int_div_zero 0
	.end_amdhsa_kernel

; __global__ void __launch_bounds__(NTHR, 2) hybrid_fwd(Args a) {
amdhsa.kernels:
  - .agpr_count:     0
    .args:
      - .offset:         0
        .size:           144
        .value_kind:     by_value
      - .offset:         144
        .size:           4
        .value_kind:     hidden_block_count_x
      - .offset:         148
        .size:           4
        .value_kind:     hidden_block_count_y
      - .offset:         152
        .size:           4
        .value_kind:     hidden_block_count_z
      - .offset:         156
        .size:           2
        .value_kind:     hidden_group_size_x
      - .offset:         158
        .size:           2
        .value_kind:     hidden_group_size_y
      - .offset:         160
        .size:           2
        .value_kind:     hidden_group_size_z
      - .offset:         162
        .size:           2
        .value_kind:     hidden_remainder_x
      - .offset:         164
        .size:           2
        .value_kind:     hidden_remainder_y
      - .offset:         166
        .size:           2
        .value_kind:     hidden_remainder_z
      - .offset:         184
        .size:           8
        .value_kind:     hidden_global_offset_x
      - .offset:         192
        .size:           8
        .value_kind:     hidden_global_offset_y
      - .offset:         200
        .size:           8
        .value_kind:     hidden_global_offset_z
      - .offset:         208
        .size:           2
        .value_kind:     hidden_grid_dims
      - .offset:         264
        .size:           4
        .value_kind:     hidden_dynamic_lds_size
    .group_segment_fixed_size: 0
    .kernarg_segment_align: 8
    .kernarg_segment_size: 400
    .language:       OpenCL C
    .language_version:
      - 2
      - 0
    .max_flat_workgroup_size: 512
    .name:           _Z10hybrid_fwd4Args
    .private_segment_fixed_size: 0
    .sgpr_count:     108
    .sgpr_spill_count: 2
    .symbol:         _Z10hybrid_fwd4Args.kd
    .uniform_work_group_size: 1
    .uses_dynamic_stack: false
    .vgpr_count:     256
    .vgpr_spill_count: 0
    .wavefront_size: 64
